# b8 + workgroup stagger (4 groups x 7us) at UP0/UP1 phase start to de-burst epilogue stores
# baseline (speedup 1.0000x reference)
.LBB0_438:
	s_lshr_b32 s98, s33, 3
	s_and_b32 s98, s98, 3
	s_mul_i32 s98, s98, 700
	s_memrealtime s[100:101]
	s_waitcnt lgkmcnt(0)
	s_add_u32 s99, s100, s98
.Lfa_skew0:
	s_sleep 2
	s_memrealtime s[100:101]
	s_waitcnt lgkmcnt(0)
	s_sub_u32 s101, s100, s99
	s_cmp_lt_i32 s101, 0
	s_cbranch_scc1 .Lfa_skew0
	s_cmp_lt_i32 s46, 6
	s_cselect_b64 s[0:1], -1, 0
	s_add_u32 s24, s44, 0xb800000
	s_addc_u32 s25, s45, 0
	s_and_b64 s[0:1], s[0:1], s[2:3]
	s_andn2_b64 vcc, exec, s[0:1]
	s_cbranch_vccnz .LBB0_477
	s_ashr_i32 s2, s66, 31
	s_lshr_b32 s2, s2, 29
	s_add_i32 s8, s66, s2
	s_and_b32 s2, s8, -8
	s_cmp_ge_i32 s33, s2
	s_cselect_b64 s[2:3], -1, 0
	s_cmpk_gt_i32 s33, 0x2bf
	s_cselect_b64 s[4:5], -1, 0
	v_mov_b32_e32 v14, v188
	s_or_b64 s[2:3], s[4:5], s[2:3]
	s_and_b64 vcc, exec, s[2:3]
	v_readfirstlane_b32 s16, v14
	s_cbranch_vccnz .LBB0_477
	s_ashr_i32 s2, s33, 31
	s_lshr_b32 s2, s2, 29
	s_add_i32 s6, s33, s2
	s_movk_i32 s2, 0xc0
	s_ashr_i32 s17, s6, 3
	s_ashr_i32 s10, s6, 5
	v_cmp_gt_u32_e64 s[2:3], s2, v188
	v_mov_b32_e32 v191, 0
	v_mov_b32_e32 v0, 0
	s_waitcnt lgkmcnt(0)
	v_mov_b32_e32 v1, 0
	v_mov_b32_e32 v2, 0
	v_mov_b32_e32 v3, 0
	s_and_saveexec_b64 s[4:5], s[2:3]
	s_cbranch_execz .LBB0_442
	v_lshrrev_b32_e32 v0, 5, v188
	s_movk_i32 s9, 0x60
	v_readlane_b32 s44, v235, 5
	v_add_u32_e32 v1, -3, v0
	v_cmp_gt_u32_e32 vcc, s9, v188
	v_readlane_b32 s58, v235, 19
	v_readlane_b32 s59, v235, 20
	s_movk_i32 s7, 0x5f
	v_cndmask_b32_e32 v2, v1, v0, vcc
	s_movk_i32 s9, 0x5800
	v_mov_b64_e32 v[0:1], s[58:59]
	v_mad_u64_u32 v[0:1], s[12:13], v2, s9, v[0:1]
	v_mov_b32_e32 v2, 0x2c00
	v_cmp_lt_u32_e32 vcc, s7, v188
	v_mov_b32_e32 v3, 0
	s_lshl_b32 s12, s10, 7
	v_cndmask_b32_e32 v2, 0, v2, vcc
	v_lshl_add_u64 v[0:1], v[0:1], 0, v[2:3]
	s_ashr_i32 s13, s12, 31
	v_lshlrev_b32_e32 v2, 4, v188
	v_lshl_add_u64 v[0:1], s[12:13], 2, v[0:1]
	v_and_b32_e32 v2, 0x1f0, v2
	v_lshl_add_u64 v[0:1], v[0:1], 0, v[2:3]
	global_load_dwordx4 v[0:3], v[0:1], off
	v_readlane_b32 s45, v235, 6
	v_readlane_b32 s46, v235, 7
	v_readlane_b32 s47, v235, 8
	v_readlane_b32 s44, v235, 29
	v_readlane_b32 s45, v235, 30
	v_readlane_b32 s46, v235, 31
	v_readlane_b32 s47, v235, 32
	v_readlane_b32 s48, v235, 9
	v_readlane_b32 s49, v235, 10
	v_readlane_b32 s50, v235, 11
	v_readlane_b32 s51, v235, 12
	v_readlane_b32 s52, v235, 13
	v_readlane_b32 s53, v235, 14
	v_readlane_b32 s54, v235, 15
	v_readlane_b32 s55, v235, 16
	v_readlane_b32 s56, v235, 17
	v_readlane_b32 s57, v235, 18

.Lfa_skew1:
	s_sleep 2
	s_memrealtime s[100:101]
	s_waitcnt lgkmcnt(0)
	s_sub_u32 s101, s100, s99
	s_cmp_lt_i32 s101, 0
	s_cbranch_scc1 .Lfa_skew1
	s_cmp_lt_i32 s46, 13
	s_cselect_b64 s[0:1], -1, 0
	s_and_b64 s[0:1], s[0:1], s[2:3]
	s_andn2_b64 vcc, exec, s[0:1]
	s_cbranch_vccnz .LBB0_1664
	s_ashr_i32 s2, s66, 31
	s_lshr_b32 s2, s2, 29
	s_add_i32 s18, s66, s2
	s_and_b32 s2, s18, -8
	s_cmp_ge_i32 s33, s2
	s_cselect_b64 s[2:3], -1, 0
	s_cmpk_gt_i32 s33, 0x2bf
	s_cselect_b64 s[4:5], -1, 0
	v_mov_b32_e32 v14, v188
	s_or_b64 s[2:3], s[4:5], s[2:3]
	s_and_b64 vcc, exec, s[2:3]
	v_readfirstlane_b32 s36, v14
	s_cbranch_vccnz .LBB0_1664
	s_ashr_i32 s2, s33, 31
	s_lshr_b32 s2, s2, 29
	v_readlane_b32 s40, v235, 5
	s_add_i32 s6, s33, s2
	v_readlane_b32 s54, v235, 19
	v_readlane_b32 s55, v235, 20
	s_ashr_i32 s37, s6, 3
	s_mov_b64 s[14:15], s[54:55]
	s_add_u32 s8, s14, 0x10800
	s_movk_i32 s2, 0xc0
	s_addc_u32 s9, s15, 0
	s_ashr_i32 s10, s6, 5
	v_cmp_gt_u32_e64 s[2:3], s2, v188
	v_mov_b32_e32 v191, 0
	v_lshrrev_b32_e32 v15, 5, v188
	s_waitcnt vmcnt(0) lgkmcnt(0)
	v_lshlrev_b32_e32 v16, 4, v188
	v_mov_b32_e32 v0, 0
	v_mov_b32_e32 v1, 0
	v_mov_b32_e32 v2, 0
	v_mov_b32_e32 v3, 0
	v_readlane_b32 s41, v235, 6
	v_readlane_b32 s42, v235, 7
	v_readlane_b32 s43, v235, 8
	v_readlane_b32 s44, v235, 9
	v_readlane_b32 s45, v235, 10
	v_readlane_b32 s46, v235, 11
	v_readlane_b32 s47, v235, 12
	v_readlane_b32 s48, v235, 13
	v_readlane_b32 s49, v235, 14
	v_readlane_b32 s50, v235, 15
	v_readlane_b32 s51, v235, 16
	v_readlane_b32 s52, v235, 17
	v_readlane_b32 s53, v235, 18
	s_and_saveexec_b64 s[4:5], s[2:3]
	s_cbranch_execz .LBB0_1629
	s_movk_i32 s11, 0x60
	v_add_u32_e32 v0, -3, v15
	v_cmp_gt_u32_e32 vcc, s11, v188
	s_movk_i32 s7, 0x5f
	s_movk_i32 s11, 0x5800
	v_cndmask_b32_e32 v2, v0, v15, vcc
	v_mov_b64_e32 v[0:1], s[8:9]
	v_mad_u64_u32 v[0:1], s[12:13], v2, s11, v[0:1]
	v_mov_b32_e32 v2, 0x2c00
	v_cmp_lt_u32_e32 vcc, s7, v188
	v_mov_b32_e32 v3, 0
	s_lshl_b32 s12, s10, 7
	v_cndmask_b32_e32 v2, 0, v2, vcc
	v_lshl_add_u64 v[0:1], v[0:1], 0, v[2:3]
	s_ashr_i32 s13, s12, 31
	v_lshl_add_u64 v[0:1], s[12:13], 2, v[0:1]
	v_and_b32_e32 v2, 0x1f0, v16
	v_lshl_add_u64 v[0:1], v[0:1], 0, v[2:3]
	global_load_dwordx4 v[0:3], v[0:1], off
